# MLA flash loop: rotating 3-buffer LDS fragment prefetch, in-place exp, softmax interleaved with PV MFMAs (on top of v8)
# speedup vs baseline: 1.0131x; 1.0051x over previous
.LBB0_796:
	v_lshl_add_u64 v[64:65], v[206:207], 0, s[4:5]
	s_waitcnt vmcnt(0)
	ds_write_b128 v202, v[180:183]
	ds_write_b128 v202, v[176:179] offset:64
	ds_write_b128 v202, v[172:175] offset:128
	ds_write_b128 v202, v[168:171] offset:192
	ds_write_b128 v202, v[164:167] offset:256
	ds_write_b128 v202, v[160:163] offset:320
	ds_write_b128 v204, v[156:159] offset:25600
	ds_write_b128 v204, v[152:155] offset:25616
	ds_write_b128 v204, v[148:151] offset:25632
	ds_write_b128 v204, v[144:147] offset:25648
	s_waitcnt lgkmcnt(0)
	s_barrier
	global_load_dwordx4 v[180:183], v[208:209], off offset:-192
	global_load_dwordx4 v[176:179], v[208:209], off offset:-128
	global_load_dwordx4 v[172:175], v[208:209], off offset:-64
	global_load_dwordx4 v[168:171], v[208:209], off
	global_load_dwordx4 v[164:167], v[208:209], off offset:64
	global_load_dwordx4 v[160:163], v[208:209], off offset:128
	global_load_dwordx4 v[144:147], v[64:65], off offset:16
	global_load_dwordx4 v[148:151], v[64:65], off
	global_load_dwordx4 v[152:155], v[64:65], off offset:-16
	global_load_dwordx4 v[156:159], v[64:65], off offset:-32
	ds_read_b128 v[212:215], v203
	ds_read_b128 v[216:219], v203 offset:32
	ds_read_b128 v[246:249], v203 offset:64
	s_waitcnt lgkmcnt(2)
	v_mfma_f32_32x32x16_bf16 v[64:79], v[212:215], v[140:143], 0
	ds_read_b128 v[212:215], v203 offset:96
	s_waitcnt lgkmcnt(2)
	v_mfma_f32_32x32x16_bf16 v[64:79], v[216:219], v[136:139], v[64:79]
	ds_read_b128 v[216:219], v203 offset:128
	s_waitcnt lgkmcnt(2)
	v_mfma_f32_32x32x16_bf16 v[64:79], v[246:249], v[132:135], v[64:79]
	ds_read_b128 v[246:249], v203 offset:160
	s_waitcnt lgkmcnt(2)
	v_mfma_f32_32x32x16_bf16 v[64:79], v[212:215], v[128:131], v[64:79]
	ds_read_b128 v[212:215], v203 offset:192
	s_waitcnt lgkmcnt(2)
	v_mfma_f32_32x32x16_bf16 v[64:79], v[216:219], v[124:127], v[64:79]
	ds_read_b128 v[216:219], v203 offset:224
	s_waitcnt lgkmcnt(2)
	v_mfma_f32_32x32x16_bf16 v[64:79], v[246:249], v[120:123], v[64:79]
	ds_read_b128 v[246:249], v203 offset:256
	s_waitcnt lgkmcnt(2)
	v_mfma_f32_32x32x16_bf16 v[64:79], v[212:215], v[116:119], v[64:79]
	ds_read_b128 v[212:215], v203 offset:288
	s_waitcnt lgkmcnt(2)
	v_mfma_f32_32x32x16_bf16 v[64:79], v[216:219], v[112:115], v[64:79]
	ds_read_b128 v[216:219], v203 offset:320
	s_waitcnt lgkmcnt(2)
	v_mfma_f32_32x32x16_bf16 v[64:79], v[246:249], v[108:111], v[64:79]
	ds_read_b128 v[246:249], v203 offset:352
	s_waitcnt lgkmcnt(2)
	v_mfma_f32_32x32x16_bf16 v[64:79], v[212:215], v[104:107], v[64:79]
	ds_read_b128 v[212:215], v203 offset:12800
	s_waitcnt lgkmcnt(2)
	v_mfma_f32_32x32x16_bf16 v[64:79], v[216:219], v[100:103], v[64:79]
	ds_read_b128 v[216:219], v203 offset:12832
	s_waitcnt lgkmcnt(2)
	v_mfma_f32_32x32x16_bf16 v[64:79], v[246:249], v[96:99], v[64:79]
	ds_read_b128 v[246:249], v203 offset:12864
	s_waitcnt lgkmcnt(2)
	v_mfma_f32_32x32x16_bf16 v[80:95], v[212:215], v[140:143], 0
	ds_read_b128 v[212:215], v203 offset:12896
	s_waitcnt lgkmcnt(2)
	v_mfma_f32_32x32x16_bf16 v[80:95], v[216:219], v[136:139], v[80:95]
	ds_read_b128 v[216:219], v203 offset:12928
	s_waitcnt lgkmcnt(2)
	v_mfma_f32_32x32x16_bf16 v[80:95], v[246:249], v[132:135], v[80:95]
	ds_read_b128 v[246:249], v203 offset:12960
	s_waitcnt lgkmcnt(2)
	v_mfma_f32_32x32x16_bf16 v[80:95], v[212:215], v[128:131], v[80:95]
	ds_read_b128 v[212:215], v203 offset:12992
	s_waitcnt lgkmcnt(2)
	v_mfma_f32_32x32x16_bf16 v[80:95], v[216:219], v[124:127], v[80:95]
	ds_read_b128 v[216:219], v203 offset:13024
	s_waitcnt lgkmcnt(2)
	v_mfma_f32_32x32x16_bf16 v[80:95], v[246:249], v[120:123], v[80:95]
	ds_read_b128 v[246:249], v203 offset:13056
	s_waitcnt lgkmcnt(2)
	v_mfma_f32_32x32x16_bf16 v[80:95], v[212:215], v[116:119], v[80:95]
	ds_read_b128 v[212:215], v203 offset:13088
	s_waitcnt lgkmcnt(2)
	v_mfma_f32_32x32x16_bf16 v[80:95], v[216:219], v[112:115], v[80:95]
	ds_read_b128 v[216:219], v203 offset:13120
	s_waitcnt lgkmcnt(2)
	v_mfma_f32_32x32x16_bf16 v[80:95], v[246:249], v[108:111], v[80:95]
	ds_read_b128 v[246:249], v203 offset:13152
	s_waitcnt lgkmcnt(2)
	v_mfma_f32_32x32x16_bf16 v[80:95], v[212:215], v[104:107], v[80:95]
	ds_read_b128 v[212:215], v190 offset:25600
	s_waitcnt lgkmcnt(2)
	v_mfma_f32_32x32x16_bf16 v[80:95], v[216:219], v[100:103], v[80:95]
	ds_read_b128 v[216:219], v190 offset:30208
	s_waitcnt lgkmcnt(2)
	v_mfma_f32_32x32x16_bf16 v[80:95], v[246:249], v[96:99], v[80:95]
	ds_read_b128 v[246:249], v190 offset:34816
	v_max_f32_e32 v205, v65, v65
	v_max_f32_e32 v211, v64, v64
	v_max_f32_e32 v205, v211, v205
	v_max3_f32 v205, v205, v66, v67
	v_max3_f32 v205, v205, v68, v69
	v_max3_f32 v205, v205, v70, v71
	v_max3_f32 v205, v205, v72, v73
	v_max3_f32 v205, v205, v74, v75
	v_max3_f32 v205, v205, v76, v77
	v_max3_f32 v205, v205, v78, v79
	s_nop 1
	v_max3_f32 v205, v205, v80, v81
	v_max3_f32 v205, v205, v82, v83
	v_max3_f32 v205, v205, v84, v85
	v_max3_f32 v205, v205, v86, v87
	v_max3_f32 v205, v205, v88, v89
	v_max3_f32 v205, v205, v90, v91
	v_max3_f32 v205, v205, v92, v93
	v_max3_f32 v205, v205, v94, v95
	ds_bpermute_b32 v211, v199, v205
	s_waitcnt lgkmcnt(0)
	v_max_f32_e32 v211, v211, v211
	v_max_f32_e32 v205, v205, v211
	v_mul_f32_e32 v205, 0x3dd53b94, v205
	v_max_f32_e32 v211, v210, v210
	v_max_f32_e32 v205, v211, v205
	v_cmp_gt_f32_e32 vcc, v205, v210
	s_cbranch_vccz .LBB0_798
	v_sub_f32_e32 v210, v210, v205
	v_exp_f32_e32 v210, v210
	s_nop 0
	v_mul_f32_e32 v201, v201, v210
	v_pk_mul_f32 v[62:63], v[62:63], v[210:211] op_sel_hi:[1,0]
	v_pk_mul_f32 v[60:61], v[60:61], v[210:211] op_sel_hi:[1,0]
	v_pk_mul_f32 v[58:59], v[58:59], v[210:211] op_sel_hi:[1,0]
	v_pk_mul_f32 v[56:57], v[56:57], v[210:211] op_sel_hi:[1,0]
	v_pk_mul_f32 v[54:55], v[54:55], v[210:211] op_sel_hi:[1,0]
	v_pk_mul_f32 v[52:53], v[52:53], v[210:211] op_sel_hi:[1,0]
	v_pk_mul_f32 v[50:51], v[50:51], v[210:211] op_sel_hi:[1,0]
	v_pk_mul_f32 v[48:49], v[48:49], v[210:211] op_sel_hi:[1,0]
	v_pk_mul_f32 v[46:47], v[46:47], v[210:211] op_sel_hi:[1,0]
	v_pk_mul_f32 v[44:45], v[44:45], v[210:211] op_sel_hi:[1,0]
	v_pk_mul_f32 v[42:43], v[42:43], v[210:211] op_sel_hi:[1,0]
	v_pk_mul_f32 v[40:41], v[40:41], v[210:211] op_sel_hi:[1,0]
	v_pk_mul_f32 v[38:39], v[38:39], v[210:211] op_sel_hi:[1,0]
	v_pk_mul_f32 v[36:37], v[36:37], v[210:211] op_sel_hi:[1,0]
	v_pk_mul_f32 v[34:35], v[34:35], v[210:211] op_sel_hi:[1,0]
	v_pk_mul_f32 v[32:33], v[32:33], v[210:211] op_sel_hi:[1,0]
	v_pk_mul_f32 v[30:31], v[30:31], v[210:211] op_sel_hi:[1,0]
	v_pk_mul_f32 v[28:29], v[28:29], v[210:211] op_sel_hi:[1,0]
	v_pk_mul_f32 v[26:27], v[26:27], v[210:211] op_sel_hi:[1,0]
	v_pk_mul_f32 v[24:25], v[24:25], v[210:211] op_sel_hi:[1,0]
	v_pk_mul_f32 v[22:23], v[22:23], v[210:211] op_sel_hi:[1,0]
	v_pk_mul_f32 v[20:21], v[20:21], v[210:211] op_sel_hi:[1,0]
	v_pk_mul_f32 v[18:19], v[18:19], v[210:211] op_sel_hi:[1,0]
	v_pk_mul_f32 v[16:17], v[16:17], v[210:211] op_sel_hi:[1,0]
	v_pk_mul_f32 v[14:15], v[14:15], v[210:211] op_sel_hi:[1,0]
	v_pk_mul_f32 v[12:13], v[12:13], v[210:211] op_sel_hi:[1,0]
	v_pk_mul_f32 v[10:11], v[10:11], v[210:211] op_sel_hi:[1,0]
	v_pk_mul_f32 v[8:9], v[8:9], v[210:211] op_sel_hi:[1,0]
	v_pk_mul_f32 v[6:7], v[6:7], v[210:211] op_sel_hi:[1,0]
	v_pk_mul_f32 v[4:5], v[4:5], v[210:211] op_sel_hi:[1,0]
	v_pk_mul_f32 v[2:3], v[2:3], v[210:211] op_sel_hi:[1,0]
	v_pk_mul_f32 v[0:1], v[0:1], v[210:211] op_sel_hi:[1,0]
.LBB0_798:
	v_fma_f32 v64, v64, s37, -v205
	v_exp_f32_e32 v64, v64
	v_fma_f32 v65, v65, s37, -v205
	v_exp_f32_e32 v65, v65
	v_fma_f32 v66, v66, s37, -v205
	v_exp_f32_e32 v66, v66
	v_add_f32_e32 v210, 0, v64
	v_fma_f32 v67, v67, s37, -v205
	v_exp_f32_e32 v67, v67
	v_add_f32_e32 v210, v65, v210
	v_fma_f32 v68, v68, s37, -v205
	v_exp_f32_e32 v68, v68
	v_add_f32_e32 v210, v66, v210
	v_add_f32_e32 v210, v67, v210
	v_fma_f32 v69, v69, s37, -v205
	v_exp_f32_e32 v69, v69
	v_fma_f32 v70, v70, s37, -v205
	v_exp_f32_e32 v70, v70
	v_add_f32_e32 v210, v68, v210
	v_fma_f32 v71, v71, s37, -v205
	v_exp_f32_e32 v71, v71
	v_add_f32_e32 v210, v69, v210
	v_add_f32_e32 v210, v70, v210
	v_add_f32_e32 v210, v71, v210
	v_cvt_pk_bf16_f32 v64, v64, v65
	v_cvt_pk_bf16_f32 v65, v66, v67
	v_cvt_pk_bf16_f32 v66, v68, v69
	v_cvt_pk_bf16_f32 v67, v70, v71
	s_nop 1
	v_mfma_f32_32x32x16_bf16 v[48:63], v[212:215], v[64:67], v[48:63]
	ds_read_b128 v[212:215], v190 offset:39424
	v_fma_f32 v72, v72, s37, -v205
	v_exp_f32_e32 v72, v72
	v_fma_f32 v73, v73, s37, -v205
	v_exp_f32_e32 v73, v73
	v_fma_f32 v74, v74, s37, -v205
	v_exp_f32_e32 v74, v74
	v_add_f32_e32 v210, v72, v210
	v_mfma_f32_32x32x16_bf16 v[32:47], v[216:219], v[64:67], v[32:47]
	ds_read_b128 v[216:219], v190 offset:25632
	v_fma_f32 v75, v75, s37, -v205
	v_exp_f32_e32 v75, v75
	v_add_f32_e32 v210, v73, v210
	v_fma_f32 v76, v76, s37, -v205
	v_exp_f32_e32 v76, v76
	v_add_f32_e32 v210, v74, v210
	v_add_f32_e32 v210, v75, v210
	v_mfma_f32_32x32x16_bf16 v[16:31], v[246:249], v[64:67], v[16:31]
	ds_read_b128 v[246:249], v190 offset:30240
	v_fma_f32 v77, v77, s37, -v205
	v_exp_f32_e32 v77, v77
	v_fma_f32 v78, v78, s37, -v205
	v_exp_f32_e32 v78, v78
	v_add_f32_e32 v210, v76, v210
	v_fma_f32 v79, v79, s37, -v205
	v_exp_f32_e32 v79, v79
	s_waitcnt lgkmcnt(2)
	v_mfma_f32_32x32x16_bf16 v[0:15], v[212:215], v[64:67], v[0:15]
	ds_read_b128 v[212:215], v190 offset:34848
	v_add_f32_e32 v210, v77, v210
	v_add_f32_e32 v210, v78, v210
	v_add_f32_e32 v210, v79, v210
	v_cvt_pk_bf16_f32 v72, v72, v73
	v_cvt_pk_bf16_f32 v73, v74, v75
	v_cvt_pk_bf16_f32 v74, v76, v77
	v_cvt_pk_bf16_f32 v75, v78, v79
	s_nop 1
	s_waitcnt lgkmcnt(2)
	v_mfma_f32_32x32x16_bf16 v[48:63], v[216:219], v[72:75], v[48:63]
	ds_read_b128 v[216:219], v190 offset:39456
	v_fma_f32 v80, v80, s37, -v205
	v_exp_f32_e32 v80, v80
	v_fma_f32 v81, v81, s37, -v205
	v_exp_f32_e32 v81, v81
	v_fma_f32 v82, v82, s37, -v205
	v_exp_f32_e32 v82, v82
	v_add_f32_e32 v210, v80, v210
	s_waitcnt lgkmcnt(2)
	v_mfma_f32_32x32x16_bf16 v[32:47], v[246:249], v[72:75], v[32:47]
	ds_read_b128 v[246:249], v190 offset:25664
	v_fma_f32 v83, v83, s37, -v205
	v_exp_f32_e32 v83, v83
	v_add_f32_e32 v210, v81, v210
	v_fma_f32 v84, v84, s37, -v205
	v_exp_f32_e32 v84, v84
	v_add_f32_e32 v210, v82, v210
	v_add_f32_e32 v210, v83, v210
	s_waitcnt lgkmcnt(2)
	v_mfma_f32_32x32x16_bf16 v[16:31], v[212:215], v[72:75], v[16:31]
	ds_read_b128 v[212:215], v190 offset:30272
	v_fma_f32 v85, v85, s37, -v205
	v_exp_f32_e32 v85, v85
	v_fma_f32 v86, v86, s37, -v205
	v_exp_f32_e32 v86, v86
	v_add_f32_e32 v210, v84, v210
	v_fma_f32 v87, v87, s37, -v205
	v_exp_f32_e32 v87, v87
	s_waitcnt lgkmcnt(2)
	v_mfma_f32_32x32x16_bf16 v[0:15], v[216:219], v[72:75], v[0:15]
	ds_read_b128 v[216:219], v190 offset:34880
	v_add_f32_e32 v210, v85, v210
	v_add_f32_e32 v210, v86, v210
	v_add_f32_e32 v210, v87, v210
	v_cvt_pk_bf16_f32 v80, v80, v81
	v_cvt_pk_bf16_f32 v81, v82, v83
	v_cvt_pk_bf16_f32 v82, v84, v85
	v_cvt_pk_bf16_f32 v83, v86, v87
	s_nop 1
	s_waitcnt lgkmcnt(2)
	v_mfma_f32_32x32x16_bf16 v[48:63], v[246:249], v[80:83], v[48:63]
	ds_read_b128 v[246:249], v190 offset:39488
	v_fma_f32 v88, v88, s37, -v205
	v_exp_f32_e32 v88, v88
	v_fma_f32 v89, v89, s37, -v205
	v_exp_f32_e32 v89, v89
	v_fma_f32 v90, v90, s37, -v205
	v_exp_f32_e32 v90, v90
	v_add_f32_e32 v210, v88, v210
	s_waitcnt lgkmcnt(2)
	v_mfma_f32_32x32x16_bf16 v[32:47], v[212:215], v[80:83], v[32:47]
	ds_read_b128 v[212:215], v190 offset:25696
	v_fma_f32 v91, v91, s37, -v205
	v_exp_f32_e32 v91, v91
	v_add_f32_e32 v210, v89, v210
	v_fma_f32 v92, v92, s37, -v205
	v_exp_f32_e32 v92, v92
	v_add_f32_e32 v210, v90, v210
	v_add_f32_e32 v210, v91, v210
	s_waitcnt lgkmcnt(2)
	v_mfma_f32_32x32x16_bf16 v[16:31], v[216:219], v[80:83], v[16:31]
	ds_read_b128 v[216:219], v190 offset:30304
	v_fma_f32 v93, v93, s37, -v205
	v_exp_f32_e32 v93, v93
	v_fma_f32 v94, v94, s37, -v205
	v_exp_f32_e32 v94, v94
	v_add_f32_e32 v210, v92, v210
	v_fma_f32 v95, v95, s37, -v205
	v_exp_f32_e32 v95, v95
	s_waitcnt lgkmcnt(2)
	v_mfma_f32_32x32x16_bf16 v[0:15], v[246:249], v[80:83], v[0:15]
	ds_read_b128 v[246:249], v190 offset:34912
	v_add_f32_e32 v210, v93, v210
	v_add_f32_e32 v210, v94, v210
	v_add_f32_e32 v210, v95, v210
	v_cvt_pk_bf16_f32 v88, v88, v89
	v_cvt_pk_bf16_f32 v89, v90, v91
	v_cvt_pk_bf16_f32 v90, v92, v93
	v_cvt_pk_bf16_f32 v91, v94, v95
	s_nop 1
	s_waitcnt lgkmcnt(2)
	v_mfma_f32_32x32x16_bf16 v[48:63], v[212:215], v[88:91], v[48:63]
	ds_read_b128 v[212:215], v190 offset:39520
	v_add_f32_e32 v201, v210, v201
	s_add_u32 s4, s4, 0x80
	s_addc_u32 s5, s5, 0
	s_waitcnt lgkmcnt(2)
	v_mfma_f32_32x32x16_bf16 v[32:47], v[216:219], v[88:91], v[32:47]
	s_mov_b64 s[18:19], 0x18000
	v_lshl_add_u64 v[208:209], v[208:209], 0, s[18:19]
	s_cmpk_eq_i32 s4, 0x2380
	s_waitcnt lgkmcnt(1)
	v_mfma_f32_32x32x16_bf16 v[16:31], v[246:249], v[88:91], v[16:31]
	s_waitcnt lgkmcnt(0)
	s_barrier
	v_mfma_f32_32x32x16_bf16 v[0:15], v[212:215], v[88:91], v[0:15]
	s_cbranch_scc1 .LBB0_800
	v_mov_b32_e32 v210, v205
	s_branch .LBB0_796
